# uvscan item order rebalanced (determinism check)
# speedup vs baseline: 1.0485x; 1.0063x over previous
.LBB0_173:
	s_movk_i32 s17, 0x180
	s_cmpk_lt_i32 s62, 0x80
	s_cselect_b32 s18, s17, 0x80
	s_cmpk_lt_i32 s62, 0x100
	s_cselect_b32 s18, s18, 0x400
	s_lshl_b32 s17, s18, 6
	s_add_i32 s61, s61, s17
	s_lshl_b32 s17, s18, 2
	s_add_i32 s16, s16, s17
	s_lshl_b32 s17, s18, 4
	s_add_i32 s58, s58, s17
	s_add_i32 s62, s62, s18
	s_add_i32 s60, s60, s18
	s_add_i32 s59, s59, s18
	s_add_i32 s57, s57, s18
	s_cmpk_lt_i32 s62, 0x192
	v_readlane_b32 s19, v253, 51
	s_cbranch_scc0 .LBB0_213
